# stagger using slack: in phases 1 and 9 the workgroups with blockIdx>=128 (which have one tile less) are the delayed group (7us / 3.5us), other phases as config E
# baseline (speedup 1.0000x reference)
;   DI bf16_t* wt_in0() const { return (bf16_t*)(ws + OFF_WT_IN0); }
;   DI bf16_t* h() const { return (bf16_t*)(ws + OFF_H); }
; DI void phase_gemm_in0(const Params& p, char* smem) {
;   u32x4 ra[4], rb[4]; bool pre = false;
;   for (int t = blockIdx.x; t < 64 * 16; t += gridDim.x) {
;     const int mt = t & 63, nt = t >> 6, tn = t + gridDim.x;
;     const bool has_next = tn < 64 * 16;
;     const GTile tl{p.h(), D, p.wt_in0(), D, D, mt * 256, nt * 256}, nx{p.h(), D, p.wt_in0(), D, D, (tn & 63) * 256, (tn >> 6) * 256};
.Lgs_185:
	s_or_b64 exec, exec, s[0:1]
	s_bitcmp1_b32 s84, 7
	s_cbranch_scc0 .Lstag_1_0
	s_sleep 127
	s_sleep 127

; DI void phase_up(const Params& p, char* smem) {
;   float* rs = (float*)(smem + G_RSTD_OFF);
;   u32x4 ra[4], rb[4]; bool pre = false;
;   int rs_key = -1;
;   for (int t = blockIdx.x; t < 64 * 14; t += gridDim.x) {
;     const int mt = t & 63, nt = t >> 6, tn = t + gridDim.x;
;     const bool has_next = tn < 64 * 14;
;     const GTile tl = up_tile(p, t), nx = up_tile(p, has_next ? tn : t);
.LBB0_968:
	s_or_b64 exec, exec, s[0:1]
	s_bitcmp1_b32 s84, 7
	s_cbranch_scc0 .Lstag_9_0
	s_sleep 127
